# UP unit loops: tile-index decode divides by the constant row-group size 8 with shift/mask instead of a software integer division
# speedup vs baseline: 1.0011x; 1.0007x over previous
.LBB0_554:
	s_add_i32 s13, s29, 1
	s_mul_i32 s3, s13, s6
	s_mul_hi_u32 s4, s13, s33
	s_add_i32 s4, s4, s3
	s_mul_i32 s3, s13, s33
	s_add_u32 s42, s3, s2
	s_addc_u32 s43, s4, s92
	v_cmp_gt_i64_e32 vcc, s[42:43], v[192:193]
	v_cmp_lt_i64_e64 s[4:5], s[42:43], v[190:191]
	s_cbranch_vccnz .LBB0_556
	s_ashr_i32 s3, s42, 31
	s_lshr_b32 s3, s3, 29
	s_add_i32 s3, s42, s3
	s_ashr_i32 s7, s3, 3
	s_and_b32 s3, s3, -8
	s_sub_i32 s3, s42, s3
	s_cmp_lt_i32 s3, 0
	s_movk_i32 s38, 0xb1
	s_cselect_b32 s38, s38, 0xb0
	s_mul_i32 s3, s3, s38
	s_add_i32 s3, s3, s7
	s_mul_hi_i32 s7, s3, 0x2e8ba2e9
	s_lshr_b32 s38, s7, 31
	s_ashr_i32 s7, s7, 5
	s_add_i32 s7, s7, s38
	s_lshl_b32 s39, s7, 3
	s_mulk_i32 s7, 0xb0
	s_sub_i32 s3, s3, s7
	s_ashr_i32 s38, s3, 3
	s_and_b32 s3, s3, 7
	s_add_i32 s40, s39, s3

.LBB0_1314:
	s_add_i32 s87, s31, 1
	s_mul_i32 s4, s87, s73
	s_mul_hi_u32 s5, s87, s33
	s_add_i32 s5, s5, s4
	s_mul_i32 s4, s87, s33
	s_add_u32 s46, s4, s2
	s_addc_u32 s47, s5, s74
	v_cmp_gt_i64_e32 vcc, s[46:47], v[194:195]
	v_cmp_lt_i64_e64 s[4:5], s[46:47], v[192:193]
	s_cbranch_vccnz .LBB0_1316
	s_ashr_i32 s42, s46, 31
	s_lshr_b32 s42, s42, 29
	s_add_i32 s42, s46, s42
	s_ashr_i32 s43, s42, 3
	s_and_b32 s42, s42, -8
	s_sub_i32 s42, s46, s42
	s_cmp_lt_i32 s42, 0
	s_movk_i32 s44, 0xb1
	s_cselect_b32 s44, s44, 0xb0
	s_mul_i32 s42, s42, s44
	s_add_i32 s42, s42, s43
	s_mul_hi_i32 s43, s42, 0x2e8ba2e9
	s_lshr_b32 s44, s43, 31
	s_ashr_i32 s43, s43, 5
	s_add_i32 s43, s43, s44
	s_lshl_b32 s44, s43, 3
	s_mulk_i32 s43, 0xb0
	s_sub_i32 s43, s42, s43
	s_ashr_i32 s42, s43, 3
	s_and_b32 s43, s43, 7
	s_add_i32 s44, s44, s43
